# attn: K/V LDS stores interleaved into the row-sum chain's wait-state slots (5 fewer s_nop + 3 fewer s_waitcnt per tile), unconditional K store in second half
# speedup vs baseline: 1.0306x; 1.0023x over previous
.LBB0_865:
	v_pk_add_f32 v[2:3], v[198:199], v[2:3]
	s_waitcnt vmcnt(0)
	v_pk_add_f32 v[2:3], v[222:223], v[2:3]
	ds_write_b128 v211, v[28:31]
	v_pk_add_f32 v[2:3], v[224:225], v[2:3]
	ds_write_b128 v211, v[32:35] offset:128
	v_pk_add_f32 v[2:3], v[122:123], v[2:3]
	ds_write_b128 v213, v[4:7] offset:53248
	v_pk_add_f32 v[2:3], v[226:227], v[2:3]
	ds_write_b128 v213, v[12:15] offset:53376
	v_pk_add_f32 v[2:3], v[110:111], v[2:3]
	s_nop 0
	v_pk_add_f32 v[2:3], v[228:229], v[2:3]
	s_nop 0
	v_pk_add_f32 v[2:3], v[100:101], v[2:3]
	s_nop 0
	v_pk_add_f32 v[2:3], v[96:97], v[2:3]
	s_nop 0
	v_pk_add_f32 v[2:3], v[230:231], v[2:3]
	s_nop 0
	v_pk_add_f32 v[2:3], v[232:233], v[2:3]
	s_nop 0
	v_pk_add_f32 v[2:3], v[78:79], v[2:3]
	s_nop 0
	v_pk_add_f32 v[2:3], v[234:235], v[2:3]
	s_nop 0
	v_pk_add_f32 v[2:3], v[66:67], v[2:3]
	s_nop 0
	v_pk_add_f32 v[2:3], v[236:237], v[2:3]
	s_nop 0
	v_pk_add_f32 v[198:199], v[54:55], v[2:3]
.LBB0_866:
	s_waitcnt lgkmcnt(0)
	s_barrier
	s_cmp_lt_u32 s89, s82
	s_cbranch_scc0 .Lq1_h2_nok
	v_add_co_u32_e32 v2, vcc, 0xfbf04000, v202
	s_nop 1
	v_addc_co_u32_e32 v3, vcc, -1, v203, vcc
	global_load_dwordx4 v[28:31], v[2:3], off offset:-128
	global_load_dwordx4 v[32:35], v[2:3], off

.LBB0_881:
	v_pk_add_f32 v[2:3], v[198:199], v[2:3]
	s_waitcnt vmcnt(0)
	v_pk_add_f32 v[2:3], v[222:223], v[2:3]
	ds_write_b128 v211, v[28:31] offset:35840
	v_pk_add_f32 v[2:3], v[224:225], v[2:3]
	ds_write_b128 v211, v[32:35] offset:35968
	v_pk_add_f32 v[2:3], v[142:143], v[2:3]
	ds_write_b128 v213, v[4:7] offset:17408
	v_pk_add_f32 v[2:3], v[226:227], v[2:3]
	ds_write_b128 v213, v[12:15] offset:17536
	v_pk_add_f32 v[2:3], v[138:139], v[2:3]
	s_nop 0
	v_pk_add_f32 v[2:3], v[228:229], v[2:3]
	s_nop 0
	v_pk_add_f32 v[2:3], v[154:155], v[2:3]
	s_nop 0
	v_pk_add_f32 v[2:3], v[160:161], v[2:3]
	s_nop 0
	v_pk_add_f32 v[2:3], v[230:231], v[2:3]
	s_nop 0
	v_pk_add_f32 v[2:3], v[232:233], v[2:3]
	s_nop 0
	v_pk_add_f32 v[2:3], v[170:171], v[2:3]
	s_nop 0
	v_pk_add_f32 v[2:3], v[234:235], v[2:3]
	s_nop 0
	v_pk_add_f32 v[2:3], v[134:135], v[2:3]
	s_nop 0
	v_pk_add_f32 v[2:3], v[236:237], v[2:3]
	s_nop 0
	v_pk_add_f32 v[198:199], v[182:183], v[2:3]
.LBB0_882:
	s_waitcnt lgkmcnt(0)
	s_barrier
	v_lshl_add_u64 v[202:203], v[202:203], 0, s[10:11]
	s_addk_i32 s87, 0x80
	s_mov_b32 s89, s88
	s_branch .LBB0_836
.Lq1_h2_pvonly:
	ds_read_b64_tr_b16 v[64:65], v215 offset:53248
	ds_read_b64_tr_b16 v[108:109], v215 offset:53280
	ds_read_b64_tr_b16 v[120:121], v215 offset:53312
	ds_read_b64_tr_b16 v[128:129], v215 offset:53344
	ds_read_b64_tr_b16 v[66:67], v215 offset:57856
	ds_read_b64_tr_b16 v[110:111], v215 offset:57888
	ds_read_b64_tr_b16 v[122:123], v215 offset:57920
	ds_read_b64_tr_b16 v[130:131], v215 offset:57952
	s_waitcnt lgkmcnt(3)
	v_mfma_f32_16x16x32_bf16 v[124:127], v[44:47], v[64:67], v[144:147]
	v_mfma_f32_16x16x32_bf16 v[64:67], v[92:95], v[64:67], v[140:143]
	s_waitcnt lgkmcnt(2)
	v_mfma_f32_16x16x32_bf16 v[100:103], v[44:47], v[108:111], v[148:151]
	v_mfma_f32_16x16x32_bf16 v[108:111], v[92:95], v[108:111], v[136:139]
	s_waitcnt lgkmcnt(1)
	v_mfma_f32_16x16x32_bf16 v[116:119], v[44:47], v[120:123], v[156:159]
	v_mfma_f32_16x16x32_bf16 v[96:99], v[92:95], v[120:123], v[152:155]
	s_waitcnt lgkmcnt(0)
	v_mfma_f32_16x16x32_bf16 v[104:107], v[44:47], v[128:131], v[164:167]
	v_mfma_f32_16x16x32_bf16 v[76:79], v[92:95], v[128:131], v[160:163]
	ds_read_b64_tr_b16 v[120:121], v215 offset:53376
	ds_read_b64_tr_b16 v[128:129], v215 offset:53408
	ds_read_b64_tr_b16 v[88:89], v215 offset:53440
	ds_read_b64_tr_b16 v[80:81], v215 offset:53472
	ds_read_b64_tr_b16 v[122:123], v215 offset:57984
	ds_read_b64_tr_b16 v[130:131], v215 offset:58016
	ds_read_b64_tr_b16 v[90:91], v215 offset:58048
	ds_read_b64_tr_b16 v[82:83], v215 offset:58080
	s_waitcnt lgkmcnt(3)
	v_mfma_f32_16x16x32_bf16 v[52:55], v[44:47], v[120:123], v[172:175]
	v_mfma_f32_16x16x32_bf16 v[68:71], v[92:95], v[120:123], v[168:171]
	s_waitcnt lgkmcnt(2)
	v_mfma_f32_16x16x32_bf16 v[48:51], v[44:47], v[128:131], v[176:179]
	v_mfma_f32_16x16x32_bf16 v[56:59], v[92:95], v[128:131], v[132:135]
	s_waitcnt lgkmcnt(1)
	v_mfma_f32_16x16x32_bf16 v[218:221], v[44:47], v[88:91], v[184:187]
	v_mfma_f32_16x16x32_bf16 v[222:225], v[92:95], v[88:91], v[180:183]
	s_waitcnt lgkmcnt(0)
	v_mfma_f32_16x16x32_bf16 v[226:229], v[44:47], v[80:83], v[192:195]
	v_mfma_f32_16x16x32_bf16 v[230:233], v[92:95], v[80:83], v[188:191]
	ds_read_b64_tr_b16 v[120:121], v215 offset:62464
	ds_read_b64_tr_b16 v[88:89], v215 offset:62496
	ds_read_b64_tr_b16 v[80:81], v215 offset:62528
	ds_read_b64_tr_b16 v[234:235], v215 offset:62560
	ds_read_b64_tr_b16 v[122:123], v216 offset:13824
	ds_read_b64_tr_b16 v[90:91], v216 offset:13856
	ds_read_b64_tr_b16 v[82:83], v216 offset:13888
	ds_read_b64_tr_b16 v[236:237], v216 offset:13920
	s_waitcnt lgkmcnt(3)
	v_mfma_f32_16x16x32_bf16 v[128:131], v[72:75], v[120:123], v[124:127]
	v_mfma_f32_16x16x32_bf16 v[120:123], v[112:115], v[120:123], v[64:67]
	s_waitcnt lgkmcnt(2)
	v_mfma_f32_16x16x32_bf16 v[124:127], v[72:75], v[88:91], v[100:103]
	v_mfma_f32_16x16x32_bf16 v[108:111], v[112:115], v[88:91], v[108:111]
	s_waitcnt lgkmcnt(1)
	v_mfma_f32_16x16x32_bf16 v[116:119], v[72:75], v[80:83], v[116:119]
	v_mfma_f32_16x16x32_bf16 v[100:103], v[112:115], v[80:83], v[96:99]
	s_waitcnt lgkmcnt(0)
	v_mfma_f32_16x16x32_bf16 v[104:107], v[72:75], v[234:237], v[104:107]
	v_mfma_f32_16x16x32_bf16 v[96:99], v[112:115], v[234:237], v[76:79]
	ds_read_b64_tr_b16 v[64:65], v215 offset:62592
	ds_read_b64_tr_b16 v[234:235], v215 offset:62624
	ds_read_b64_tr_b16 v[238:239], v215 offset:62656
	ds_read_b64_tr_b16 v[242:243], v215 offset:62688
	ds_read_b64_tr_b16 v[66:67], v216 offset:13952
	ds_read_b64_tr_b16 v[236:237], v216 offset:13984
	ds_read_b64_tr_b16 v[240:241], v216 offset:14016
	ds_read_b64_tr_b16 v[244:245], v216 offset:14048
	s_waitcnt lgkmcnt(3)
	v_mfma_f32_16x16x32_bf16 v[88:91], v[72:75], v[64:67], v[52:55]
	v_mfma_f32_16x16x32_bf16 v[76:79], v[112:115], v[64:67], v[68:71]
	s_waitcnt lgkmcnt(2)
	v_mfma_f32_16x16x32_bf16 v[80:83], v[72:75], v[234:237], v[48:51]
	v_mfma_f32_16x16x32_bf16 v[64:67], v[112:115], v[234:237], v[56:59]
	s_waitcnt lgkmcnt(1)
	v_mfma_f32_16x16x32_bf16 v[68:71], v[72:75], v[238:241], v[218:221]
	v_mfma_f32_16x16x32_bf16 v[52:55], v[112:115], v[238:241], v[222:225]
	s_waitcnt lgkmcnt(0)
	v_mfma_f32_16x16x32_bf16 v[56:59], v[72:75], v[242:245], v[226:229]
	v_mfma_f32_16x16x32_bf16 v[48:51], v[112:115], v[242:245], v[230:233]
	s_mov_b64 s[2:3], 0
	s_waitcnt vmcnt(0)
	ds_write_b128 v211, v[28:31] offset:35840
	ds_write_b128 v211, v[32:35] offset:35968
	ds_write_b128 v213, v[4:7] offset:17408
	ds_write_b128 v213, v[12:15] offset:17536
	s_branch .LBB0_882

.LBB0_931:
	v_pk_add_f32 v[2:3], v[200:201], v[2:3]
	s_waitcnt vmcnt(0)
	v_pk_add_f32 v[2:3], v[128:129], v[2:3]
	ds_write_b128 v219, v[28:31]
	v_pk_add_f32 v[2:3], v[124:125], v[2:3]
	ds_write_b128 v219, v[32:35] offset:128
	v_pk_add_f32 v[2:3], v[120:121], v[2:3]
	ds_write_b128 v225, v[4:7] offset:53248
	v_pk_add_f32 v[2:3], v[116:117], v[2:3]
	ds_write_b128 v225, v[16:19] offset:53376
	v_pk_add_f32 v[2:3], v[112:113], v[2:3]
	s_nop 0
	v_pk_add_f32 v[2:3], v[108:109], v[2:3]
	s_nop 0
	v_pk_add_f32 v[2:3], v[104:105], v[2:3]
	s_nop 0
	v_pk_add_f32 v[2:3], v[100:101], v[2:3]
	s_nop 0
	v_pk_add_f32 v[2:3], v[92:93], v[2:3]
	s_nop 0
	v_pk_add_f32 v[2:3], v[84:85], v[2:3]
	s_nop 0
	v_pk_add_f32 v[2:3], v[80:81], v[2:3]
	s_nop 0
	v_pk_add_f32 v[2:3], v[72:73], v[2:3]
	s_nop 0
	v_pk_add_f32 v[2:3], v[68:69], v[2:3]
	s_nop 0
	v_pk_add_f32 v[2:3], v[64:65], v[2:3]
	s_nop 0
	v_pk_add_f32 v[200:201], v[60:61], v[2:3]
.LBB0_932:
	s_waitcnt lgkmcnt(0)
	s_barrier
	s_cmp_lt_u32 s82, s56
	s_cbranch_scc0 .Lq2_h2_nok
	v_add_co_u32_e32 v2, vcc, 0xfbf04000, v202
	s_nop 1
	v_addc_co_u32_e32 v3, vcc, -1, v203, vcc
	global_load_dwordx4 v[28:31], v[2:3], off offset:-128
	global_load_dwordx4 v[32:35], v[2:3], off

.LBB0_947:
	v_pk_add_f32 v[2:3], v[200:201], v[2:3]
	s_waitcnt vmcnt(0)
	v_pk_add_f32 v[2:3], v[144:145], v[2:3]
	ds_write_b128 v219, v[28:31] offset:35840
	v_pk_add_f32 v[2:3], v[140:141], v[2:3]
	ds_write_b128 v219, v[32:35] offset:35968
	v_pk_add_f32 v[2:3], v[148:149], v[2:3]
	ds_write_b128 v220, v[4:7] offset:17408
	v_pk_add_f32 v[2:3], v[136:137], v[2:3]
	ds_write_b128 v220, v[16:19] offset:17536
	v_pk_add_f32 v[2:3], v[156:157], v[2:3]
	s_nop 0
	v_pk_add_f32 v[2:3], v[152:153], v[2:3]
	s_nop 0
	v_pk_add_f32 v[2:3], v[164:165], v[2:3]
	s_nop 0
	v_pk_add_f32 v[2:3], v[160:161], v[2:3]
	s_nop 0
	v_pk_add_f32 v[2:3], v[172:173], v[2:3]
	s_nop 0
	v_pk_add_f32 v[2:3], v[168:169], v[2:3]
	s_nop 0
	v_pk_add_f32 v[2:3], v[176:177], v[2:3]
	s_nop 0
	v_pk_add_f32 v[2:3], v[132:133], v[2:3]
	s_nop 0
	v_pk_add_f32 v[2:3], v[184:185], v[2:3]
	s_nop 0
	v_pk_add_f32 v[2:3], v[180:181], v[2:3]
	s_nop 0
	v_pk_add_f32 v[200:201], v[192:193], v[2:3]
.LBB0_948:
	s_waitcnt lgkmcnt(0)
	s_barrier
	v_lshl_add_u64 v[202:203], v[202:203], 0, s[10:11]
	s_addk_i32 s80, 0x80
	s_mov_b32 s82, s81
	s_branch .LBB0_902
.Lq2_h2_pvonly:
	ds_read_b64_tr_b16 v[72:73], v222 offset:53248
	ds_read_b64_tr_b16 v[116:117], v222 offset:53280
	ds_read_b64_tr_b16 v[124:125], v222 offset:53312
	ds_read_b64_tr_b16 v[128:129], v222 offset:53344
	ds_read_b64_tr_b16 v[74:75], v222 offset:57856
	ds_read_b64_tr_b16 v[118:119], v222 offset:57888
	ds_read_b64_tr_b16 v[126:127], v222 offset:57920
	ds_read_b64_tr_b16 v[130:131], v222 offset:57952
	s_waitcnt lgkmcnt(3)
	v_mfma_f32_16x16x32_bf16 v[120:123], v[44:47], v[72:75], v[144:147]
	v_mfma_f32_16x16x32_bf16 v[72:75], v[88:91], v[72:75], v[140:143]
	s_waitcnt lgkmcnt(2)
	v_mfma_f32_16x16x32_bf16 v[108:111], v[44:47], v[116:119], v[148:151]
	v_mfma_f32_16x16x32_bf16 v[116:119], v[88:91], v[116:119], v[136:139]
	s_waitcnt lgkmcnt(1)
	v_mfma_f32_16x16x32_bf16 v[112:115], v[44:47], v[124:127], v[156:159]
	v_mfma_f32_16x16x32_bf16 v[100:103], v[88:91], v[124:127], v[152:155]
	s_waitcnt lgkmcnt(0)
	v_mfma_f32_16x16x32_bf16 v[104:107], v[44:47], v[128:131], v[164:167]
	v_mfma_f32_16x16x32_bf16 v[84:87], v[88:91], v[128:131], v[160:163]
	ds_read_b64_tr_b16 v[124:125], v222 offset:53376
	ds_read_b64_tr_b16 v[128:129], v222 offset:53408
	ds_read_b64_tr_b16 v[92:93], v222 offset:53440
	ds_read_b64_tr_b16 v[80:81], v222 offset:53472
	ds_read_b64_tr_b16 v[126:127], v222 offset:57984
	ds_read_b64_tr_b16 v[130:131], v222 offset:58016
	ds_read_b64_tr_b16 v[94:95], v222 offset:58048
	ds_read_b64_tr_b16 v[82:83], v222 offset:58080
	s_waitcnt lgkmcnt(3)
	v_mfma_f32_16x16x32_bf16 v[64:67], v[44:47], v[124:127], v[172:175]
	v_mfma_f32_16x16x32_bf16 v[68:71], v[88:91], v[124:127], v[168:171]
	s_waitcnt lgkmcnt(2)
	v_mfma_f32_16x16x32_bf16 v[52:55], v[44:47], v[128:131], v[176:179]
	v_mfma_f32_16x16x32_bf16 v[60:63], v[88:91], v[128:131], v[132:135]
	s_waitcnt lgkmcnt(1)
	v_mfma_f32_16x16x32_bf16 v[226:229], v[44:47], v[92:95], v[184:187]
	v_mfma_f32_16x16x32_bf16 v[230:233], v[88:91], v[92:95], v[180:183]
	s_waitcnt lgkmcnt(0)
	v_mfma_f32_16x16x32_bf16 v[234:237], v[44:47], v[80:83], v[192:195]
	v_mfma_f32_16x16x32_bf16 v[238:241], v[88:91], v[80:83], v[188:191]
	ds_read_b64_tr_b16 v[124:125], v222 offset:62464
	ds_read_b64_tr_b16 v[92:93], v222 offset:62496
	ds_read_b64_tr_b16 v[80:81], v222 offset:62528
	ds_read_b64_tr_b16 v[242:243], v222 offset:62560
	ds_read_b64_tr_b16 v[126:127], v223 offset:13824
	ds_read_b64_tr_b16 v[94:95], v223 offset:13856
	ds_read_b64_tr_b16 v[82:83], v223 offset:13888
	ds_read_b64_tr_b16 v[244:245], v223 offset:13920
	s_waitcnt lgkmcnt(3)
	v_mfma_f32_16x16x32_bf16 v[128:131], v[56:59], v[124:127], v[120:123]
	v_mfma_f32_16x16x32_bf16 v[124:127], v[96:99], v[124:127], v[72:75]
	s_waitcnt lgkmcnt(2)
	v_mfma_f32_16x16x32_bf16 v[120:123], v[56:59], v[92:95], v[108:111]
	v_mfma_f32_16x16x32_bf16 v[116:119], v[96:99], v[92:95], v[116:119]
	s_waitcnt lgkmcnt(1)
	v_mfma_f32_16x16x32_bf16 v[112:115], v[56:59], v[80:83], v[112:115]
	v_mfma_f32_16x16x32_bf16 v[108:111], v[96:99], v[80:83], v[100:103]
	s_waitcnt lgkmcnt(0)
	v_mfma_f32_16x16x32_bf16 v[104:107], v[56:59], v[242:245], v[104:107]
	v_mfma_f32_16x16x32_bf16 v[100:103], v[96:99], v[242:245], v[84:87]
	ds_read_b64_tr_b16 v[72:73], v222 offset:62592
	ds_read_b64_tr_b16 v[242:243], v222 offset:62624
	ds_read_b64_tr_b16 v[246:247], v222 offset:62656
	ds_read_b64_tr_b16 v[250:251], v222 offset:62688
	ds_read_b64_tr_b16 v[74:75], v223 offset:13952
	ds_read_b64_tr_b16 v[244:245], v223 offset:13984
	ds_read_b64_tr_b16 v[248:249], v223 offset:14016
	ds_read_b64_tr_b16 v[252:253], v223 offset:14048
	s_waitcnt lgkmcnt(3)
	v_mfma_f32_16x16x32_bf16 v[92:95], v[56:59], v[72:75], v[64:67]
	v_mfma_f32_16x16x32_bf16 v[84:87], v[96:99], v[72:75], v[68:71]
	s_waitcnt lgkmcnt(2)
	v_mfma_f32_16x16x32_bf16 v[80:83], v[56:59], v[242:245], v[52:55]
	v_mfma_f32_16x16x32_bf16 v[72:75], v[96:99], v[242:245], v[60:63]
	s_waitcnt lgkmcnt(1)
	v_mfma_f32_16x16x32_bf16 v[68:71], v[56:59], v[246:249], v[226:229]
	v_mfma_f32_16x16x32_bf16 v[64:67], v[96:99], v[246:249], v[230:233]
	s_waitcnt lgkmcnt(0)
	v_mfma_f32_16x16x32_bf16 v[60:63], v[56:59], v[250:253], v[234:237]
	v_mfma_f32_16x16x32_bf16 v[52:55], v[96:99], v[250:253], v[238:241]
	s_mov_b64 s[2:3], 0
	s_waitcnt vmcnt(0)
	ds_write_b128 v219, v[28:31] offset:35840
	ds_write_b128 v219, v[32:35] offset:35968
	ds_write_b128 v220, v[4:7] offset:17408
	ds_write_b128 v220, v[16:19] offset:17536
	s_branch .LBB0_948
